# attention lagging half issues its first K-fragment reads between the two halves of the previous tile's PV product
# speedup vs baseline: 1.0037x; 1.0037x over previous
; #define LAS __attribute__((address_space(3)))
; __device__ __forceinline__ unsigned cvtpk(float lo, float hi) { f32x2_t v = {lo, hi}; bf16x2_t b = __builtin_convertvector(v, bf16x2_t); return __builtin_bit_cast(unsigned, b); }
; __device__ __forceinline__ f32x4 mfma16(bf16x8 a, bf16x8 b, f32x4 c) { return __builtin_amdgcn_mfma_f32_16x16x32_bf16(a, b, c, 0, 0, 0); }
; __device__ __forceinline__ u32x2 tr_rd(const LAS bf16_t* p) { return __builtin_bit_cast(u32x2, __builtin_amdgcn_ds_read_tr16_b64_v4i16((LAS v4i16_t*)p)); }
; __device__ __forceinline__ void attn_unit(LAS unsigned char* lds, const bf16_t* Q, const bf16_t* KV, const bf16_t* KR, bf16_t* MIX, size_t qrow0, size_t krow0, int ntiles, int h, const int tid) {
;     ...
;   for (int t = 0; t < ntiles; ++t) {
;     LAS unsigned char* buf = lds + (t & 1) * AT_BUF;
;     const bool more = (t + 1 < ntiles);
;     if (more) { const bf16_t* g2 = gk + (size_t)(t + 1) * 64 * 1024; rk = *(const u32x4*)g2; rv = *(const u32x4*)(g2 + 64); if (tid < 256) rr = *(const u32x4*)(gr + (size_t)(t + 1) * 64 * 32); }
;     const LAS bf16_t* Ks = (const LAS bf16_t*)buf; const LAS bf16_t* Vs = (const LAS bf16_t*)(buf + 64 * AT_KSTR * 2);
;     f32x4 s[4][2];
; #pragma unroll
;     for (int kb = 0; kb < 4; ++kb) {
;       bf16x8 kf[3];
; #pragma unroll
;       for (int ks = 0; ks < 3; ++ks) kf[ks] = *(const LAS bf16x8*)(Ks + (kb * 16 + c16) * AT_KSTR + ks * 32 + quad * 8);
;     ...
;     for (int s2 = 0; s2 < 2; ++s2) {
;       bf16x8 pf[2];
; #pragma unroll
;       for (int qb = 0; qb < 2; ++qb) { u32x4 w; w.x = cvtpk(s[2 * s2][qb][0], s[2 * s2][qb][1]); w.y = cvtpk(s[2 * s2][qb][2], s[2 * s2][qb][3]);
;         w.z = cvtpk(s[2 * s2 + 1][qb][0], s[2 * s2 + 1][qb][1]); w.w = cvtpk(s[2 * s2 + 1][qb][2], s[2 * s2 + 1][qb][3]); pf[qb] = __builtin_bit_cast(bf16x8, w);
;         lacc[qb] = mfma16(ones, pf[qb], lacc[qb]); }
;       const LAS bf16_t* vb = Vs + (32 * s2 + 4 * quad + tq) * AT_VSTR + 4 * tp;
; #pragma unroll
;       for (int eb = 0; eb < 4; ++eb) {
;         const u32x2 lo = tr_rd(vb + 16 * eb), hi = tr_rd(vb + 16 * AT_VSTR + 16 * eb);
;         const u32x4 vv = (u32x4){lo.x, lo.y, hi.x, hi.y}; const bf16x8 vf = __builtin_bit_cast(bf16x8, vv);
; #pragma unroll
;         for (int qb = 0; qb < 2; ++qb) o[qb][eb] = mfma16(vf, pf[qb], o[qb][eb]);
;       }
;     }
.LBB0_382:
	s_or_b64 exec, exec, s[4:5]
	s_and_b32 s4, s8, 7
	s_mul_i32 s5, s4, 0x84000
	s_mul_i32 s4, s4, 0x1080000
	s_lshl_b64 s[0:1], s[0:1], 1
	s_add_u32 s0, s4, s0
	v_or_b32_e32 v0, s5, v121
	s_addc_u32 s1, 0, s1
	v_pk_add_f32 v[2:3], v[2:3], 0 op_sel_hi:[1,0]
	v_lshl_add_u64 v[140:141], v[132:133], 0, v[0:1]
	v_lshl_add_u64 v[142:143], v[134:135], 0, s[0:1]
	s_mov_b32 s4, 2
	s_waitcnt vmcnt(0)
	ds_write_b128 v151, v[72:75] offset:35840
	s_waitcnt lgkmcnt(0)
	s_barrier
	v_mov_b32_e32 v198, 0x3f803f80
	v_mov_b32_e32 v199, v198
	v_mov_b32_e32 v200, v198
	v_mov_b32_e32 v201, v198
	v_xor_b32_e32 v202, 0x80000000, v2
	v_xor_b32_e32 v206, 0x80000000, v3
	v_lshlrev_b32_e32 v176, 1, v154
	v_mov_b32_e32 v203, v202
	v_mov_b32_e32 v204, v202
	v_mov_b32_e32 v205, v202
	v_mov_b32_e32 v207, v206
	v_mov_b32_e32 v208, v206
	v_mov_b32_e32 v209, v206
	s_cmp_lg_u32 s42, 0
	s_cbranch_scc1 .LBB0_384
	global_load_dwordx4 v[76:79], v[142:143], off
	global_load_dwordx4 v[72:75], v[142:143], off offset:128
	s_add_i32 s0, s4, -1
	s_mul_i32 s1, s0, 0xaaab
	s_lshr_b32 s1, s1, 17
	s_mul_i32 s1, s1, 3
	s_sub_i32 s0, s0, s1
	s_mul_i32 s1, s0, 0x5800
	s_add_i32 s5, s1, 0x5800
	s_cmp_eq_u32 s5, 0x10800
	s_cselect_b32 s5, 0, s5
	v_add3_u32 v0, s1, v124, v146
	ds_read_b128 v[170:173], v0
	ds_read_b128 v[210:213], v0 offset:64
	ds_read_b128 v[214:217], v0 offset:128
	ds_read_b128 v[218:221], v0 offset:3328
	ds_read_b128 v[166:169], v0 offset:3392
	s_branch .Lat_B_mid
.Lat_B_top:
	global_load_dwordx4 v[76:79], v[142:143], off
	global_load_dwordx4 v[72:75], v[142:143], off offset:128
	s_add_i32 s0, s4, -1
	s_mul_i32 s1, s0, 0xaaab
	s_lshr_b32 s1, s1, 17
	s_mul_i32 s1, s1, 3
	s_sub_i32 s0, s0, s1
	s_mul_i32 s1, s0, 0x5800
	s_add_i32 s5, s1, 0x5800
	s_cmp_eq_u32 s5, 0x10800
	s_cselect_b32 s5, 0, s5
	s_add_i32 s0, s1, 0xffffa800
	s_cmp_lt_i32 s0, 0
	s_cselect_b32 s0, 0xb000, s0
	v_add3_u32 v139, s0, v176, v155
	ds_read_b64_tr_b16 v[170:171], v139 offset:13312
	ds_read_b64_tr_b16 v[172:173], v139 offset:15616
	ds_read_b64_tr_b16 v[210:211], v139 offset:13344
	ds_read_b64_tr_b16 v[212:213], v139 offset:15648
	ds_read_b64_tr_b16 v[214:215], v139 offset:13376
	ds_read_b64_tr_b16 v[216:217], v139 offset:15680
	ds_read_b64_tr_b16 v[218:219], v139 offset:13408
	ds_read_b64_tr_b16 v[220:221], v139 offset:15712
	ds_read_b64_tr_b16 v[240:241], v139 offset:17920
	ds_read_b64_tr_b16 v[242:243], v139 offset:20224
	ds_read_b64_tr_b16 v[244:245], v139 offset:17952
	ds_read_b64_tr_b16 v[246:247], v139 offset:20256
	ds_read_b64_tr_b16 v[158:159], v139 offset:17984
	ds_read_b64_tr_b16 v[160:161], v139 offset:20288
	s_waitcnt lgkmcnt(12)
	v_mfma_f32_16x16x32_bf16 v[52:55], v[170:173], v[80:83], v[52:55]
	v_mfma_f32_16x16x32_bf16 v[48:51], v[170:173], v[88:91], v[48:51]
	ds_read_b64_tr_b16 v[162:163], v139 offset:18016
	ds_read_b64_tr_b16 v[164:165], v139 offset:20320
	v_mfma_f32_16x16x32_bf16 v[60:63], v[198:201], v[80:83], v[60:63]
	v_mfma_f32_16x16x32_bf16 v[56:59], v[198:201], v[88:91], v[56:59]
	s_waitcnt lgkmcnt(12)
	v_mfma_f32_16x16x32_bf16 v[68:71], v[210:213], v[80:83], v[68:71]
	v_mfma_f32_16x16x32_bf16 v[64:67], v[210:213], v[88:91], v[64:67]
	s_waitcnt lgkmcnt(10)
	v_mfma_f32_16x16x32_bf16 v[44:47], v[214:217], v[80:83], v[44:47]
	v_mfma_f32_16x16x32_bf16 v[40:43], v[214:217], v[88:91], v[40:43]
	s_waitcnt lgkmcnt(8)
	v_mfma_f32_16x16x32_bf16 v[36:39], v[218:221], v[80:83], v[36:39]
	v_mfma_f32_16x16x32_bf16 v[32:35], v[218:221], v[88:91], v[32:35]
	v_add3_u32 v0, s1, v124, v146
	ds_read_b128 v[170:173], v0
	ds_read_b128 v[210:213], v0 offset:64
	ds_read_b128 v[214:217], v0 offset:128
	ds_read_b128 v[218:221], v0 offset:3328
	ds_read_b128 v[166:169], v0 offset:3392
	v_mfma_f32_16x16x32_bf16 v[60:63], v[198:201], v[96:99], v[60:63]
	v_mfma_f32_16x16x32_bf16 v[56:59], v[198:201], v[104:107], v[56:59]
	s_waitcnt lgkmcnt(11)
	v_mfma_f32_16x16x32_bf16 v[52:55], v[240:243], v[96:99], v[52:55]
	v_mfma_f32_16x16x32_bf16 v[48:51], v[240:243], v[104:107], v[48:51]
	s_waitcnt lgkmcnt(9)
	v_mfma_f32_16x16x32_bf16 v[68:71], v[244:247], v[96:99], v[68:71]
	v_mfma_f32_16x16x32_bf16 v[64:67], v[244:247], v[104:107], v[64:67]
	s_waitcnt lgkmcnt(7)
	v_mfma_f32_16x16x32_bf16 v[44:47], v[158:161], v[96:99], v[44:47]
	v_mfma_f32_16x16x32_bf16 v[40:43], v[158:161], v[104:107], v[40:43]
	s_waitcnt lgkmcnt(5)
	v_mfma_f32_16x16x32_bf16 v[36:39], v[162:165], v[96:99], v[36:39]
	v_mfma_f32_16x16x32_bf16 v[32:35], v[162:165], v[104:107], v[32:35]
; #define LAS __attribute__((address_space(3)))
; __device__ __forceinline__ f32x4 mfma16(bf16x8 a, bf16x8 b, f32x4 c) { return __builtin_amdgcn_mfma_f32_16x16x32_bf16(a, b, c, 0, 0, 0); }
; __device__ __forceinline__ void attn_unit(LAS unsigned char* lds, const bf16_t* Q, const bf16_t* KV, const bf16_t* KR, bf16_t* MIX, size_t qrow0, size_t krow0, int ntiles, int h, const int tid) {
;     ...
;     const LAS bf16_t* Ks = (const LAS bf16_t*)buf; const LAS bf16_t* Vs = (const LAS bf16_t*)(buf + 64 * AT_KSTR * 2);
;     f32x4 s[4][2];
; #pragma unroll
;     for (int kb = 0; kb < 4; ++kb) {
;       bf16x8 kf[3];
; #pragma unroll
;       for (int ks = 0; ks < 3; ++ks) kf[ks] = *(const LAS bf16x8*)(Ks + (kb * 16 + c16) * AT_KSTR + ks * 32 + quad * 8);
; #pragma unroll
;       for (int qb = 0; qb < 2; ++qb) { const float nm = -mref[qb]; f32x4 a = (f32x4){nm, nm, nm, nm};
; #pragma unroll
;         for (int ks = 0; ks < 3; ++ks) a = mfma16(kf[ks], qf[qb][ks], a);
;         s[kb][qb] = a; }
;     }
; #pragma unroll
;     for (int qb = 0; qb < 2; ++qb) {
;       float mx = -1e30f;
; #pragma unroll
;       for (int kb = 0; kb < 4; ++kb) mx = fmaxf(fmaxf(fmaxf(s[kb][qb][0], s[kb][qb][1]), fmaxf(s[kb][qb][2], s[kb][qb][3])), mx);
;       mx = fmaxf(mx, __shfl_xor(mx, 16)); mx = fmaxf(mx, __shfl_xor(mx, 32));
;       if (t == 0 || __any(mx > 8.f)) {
.Lat_B_mid:
	ds_read_b128 v[240:243], v0 offset:3456
	ds_read_b128 v[244:247], v0 offset:6656
	ds_read_b128 v[158:161], v0 offset:6720
	ds_read_b128 v[162:165], v0 offset:6784
	s_waitcnt lgkmcnt(8)
	v_mfma_f32_16x16x32_bf16 v[80:83], v[170:173], v[4:7], v[202:205]
	v_mfma_f32_16x16x32_bf16 v[88:91], v[170:173], v[16:19], v[206:209]
	s_waitcnt lgkmcnt(7)
	v_mfma_f32_16x16x32_bf16 v[80:83], v[210:213], v[8:11], v[80:83]
	v_mfma_f32_16x16x32_bf16 v[88:91], v[210:213], v[20:23], v[88:91]
	s_waitcnt lgkmcnt(6)
	v_mfma_f32_16x16x32_bf16 v[80:83], v[214:217], v[12:15], v[80:83]
	v_mfma_f32_16x16x32_bf16 v[88:91], v[214:217], v[24:27], v[88:91]
	ds_read_b128 v[170:173], v0 offset:9984
	ds_read_b128 v[210:213], v0 offset:10048
	ds_read_b128 v[214:217], v0 offset:10112
	s_waitcnt lgkmcnt(8)
	v_mfma_f32_16x16x32_bf16 v[84:87], v[218:221], v[4:7], v[202:205]
	v_mfma_f32_16x16x32_bf16 v[92:95], v[218:221], v[16:19], v[206:209]
	s_waitcnt lgkmcnt(7)
	v_mfma_f32_16x16x32_bf16 v[84:87], v[166:169], v[8:11], v[84:87]
	v_mfma_f32_16x16x32_bf16 v[92:95], v[166:169], v[20:23], v[92:95]
	s_waitcnt lgkmcnt(6)
	v_mfma_f32_16x16x32_bf16 v[84:87], v[240:243], v[12:15], v[84:87]
	v_mfma_f32_16x16x32_bf16 v[92:95], v[240:243], v[24:27], v[92:95]
	s_waitcnt lgkmcnt(5)
	v_mfma_f32_16x16x32_bf16 v[96:99], v[244:247], v[4:7], v[202:205]
	v_mfma_f32_16x16x32_bf16 v[104:107], v[244:247], v[16:19], v[206:209]
	v_max3_f32 v174, v80, v81, v82
	s_waitcnt lgkmcnt(4)
	v_mfma_f32_16x16x32_bf16 v[96:99], v[158:161], v[8:11], v[96:99]
	v_mfma_f32_16x16x32_bf16 v[104:107], v[158:161], v[20:23], v[104:107]
	v_max3_f32 v175, v88, v89, v90
	s_waitcnt lgkmcnt(3)
	v_mfma_f32_16x16x32_bf16 v[96:99], v[162:165], v[12:15], v[96:99]
	v_mfma_f32_16x16x32_bf16 v[104:107], v[162:165], v[24:27], v[104:107]
	s_waitcnt lgkmcnt(2)
	v_mfma_f32_16x16x32_bf16 v[100:103], v[170:173], v[4:7], v[202:205]
	v_mfma_f32_16x16x32_bf16 v[108:111], v[170:173], v[16:19], v[206:209]
	v_max3_f32 v174, v174, v83, v84
	s_waitcnt lgkmcnt(1)
	v_mfma_f32_16x16x32_bf16 v[100:103], v[210:213], v[8:11], v[100:103]
	v_max3_f32 v174, v174, v85, v86
	v_mfma_f32_16x16x32_bf16 v[108:111], v[210:213], v[20:23], v[108:111]
	s_waitcnt lgkmcnt(0)
	v_mfma_f32_16x16x32_bf16 v[100:103], v[214:217], v[12:15], v[100:103]
	v_max3_f32 v175, v175, v91, v92
	v_mfma_f32_16x16x32_bf16 v[108:111], v[214:217], v[24:27], v[108:111]
	v_max3_f32 v175, v175, v93, v94
	v_max3_f32 v174, v174, v87, v96
	v_max3_f32 v174, v174, v97, v98
	v_max3_f32 v175, v175, v95, v104
	v_max3_f32 v175, v175, v105, v106
	v_add3_u32 v0, s5, v148, v138
	v_add3_u32 v177, s5, v127, v138
	s_nop 0
	v_max3_f32 v174, v174, v99, v100
	v_max3_f32 v175, v175, v107, v108
	v_max3_f32 v174, v174, v101, v102
	v_max3_f32 v175, v175, v109, v110
	v_max_f32_e32 v174, v174, v103
	v_max_f32_e32 v175, v175, v111
	v_max_f32_e32 v235, v174, v175
	v_cmp_lt_f32_e32 vcc, 0x41000000, v235
	s_cbranch_vccnz .Lat_rareB
